# attention QK block: the two lazy-rescale thresholds (m+8) also computed inside the MFMA-result wait (s_nop 6 -> s_nop 4), removing them from the dependent chains before the branches
# baseline (speedup 1.0000x reference)
.LBB0_1046:
	s_or_b64 exec, exec, s[22:23]
	global_load_dwordx4 v[152:155], v[168:169], off
	s_and_b32 s25, s4, 1
	v_cmp_le_i32_e32 vcc, s4, v185
	s_and_saveexec_b64 s[22:23], vcc
	s_cbranch_execz .LBB0_1052
	s_mul_i32 s26, s25, 0x5600
	s_add_i32 s26, s26, 0
	v_add3_u32 v187, s26, v184, v166
	ds_read_b128 v[64:67], v187
	ds_read_b128 v[188:191], v187 offset:32
	s_waitcnt lgkmcnt(1)
	v_mfma_f32_32x32x16_bf16 v[80:95], v[64:67], v[132:135], 0
	v_mfma_f32_32x32x16_bf16 v[64:79], v[64:67], v[140:143], 0
	s_waitcnt lgkmcnt(0)
	v_mfma_f32_32x32x16_bf16 v[80:95], v[188:191], v[124:127], v[80:95]
	v_mfma_f32_32x32x16_bf16 v[64:79], v[188:191], v[136:139], v[64:79]
	ds_read_b128 v[188:191], v187 offset:64
	ds_read_b128 v[192:195], v187 offset:96
	s_waitcnt lgkmcnt(1)
	v_mfma_f32_32x32x16_bf16 v[80:95], v[188:191], v[120:123], v[80:95]
	s_waitcnt lgkmcnt(0)
	v_mfma_f32_32x32x16_bf16 v[80:95], v[192:195], v[116:119], v[80:95]
	v_mfma_f32_32x32x16_bf16 v[64:79], v[188:191], v[128:131], v[64:79]
	ds_read_b128 v[188:191], v187 offset:128
	ds_read_b128 v[196:199], v187 offset:160
	s_nop 1
	s_waitcnt lgkmcnt(1)
	v_mfma_f32_32x32x16_bf16 v[80:95], v[188:191], v[112:115], v[80:95]
	s_waitcnt lgkmcnt(0)
	v_mfma_f32_32x32x16_bf16 v[80:95], v[196:199], v[108:111], v[80:95]
	v_mfma_f32_32x32x16_bf16 v[64:79], v[192:195], v[104:107], v[64:79]
	v_lshl_add_u32 v201, v179, 1, s26
	v_add3_u32 v202, v201, v158, v178
	v_add_u32_e32 v201, 0x3000, v202
	v_add_u32_e32 v202, 0x4000, v202
	v_add_f32_e32 v203, 0x41000000, v161
	v_add_f32_e32 v204, 0x41000000, v167
	s_nop 4
	v_max_f32_e32 v200, v81, v81
	v_max_f32_e32 v192, v80, v80
	v_max_f32_e32 v192, v192, v200
	v_max3_f32 v192, v192, v82, v83
	v_max3_f32 v192, v192, v84, v85
	v_max3_f32 v192, v192, v86, v87
	v_max3_f32 v192, v192, v88, v89
	v_mfma_f32_32x32x16_bf16 v[64:79], v[188:191], v[100:103], v[64:79]
	v_max3_f32 v192, v192, v90, v91
	v_max3_f32 v188, v192, v92, v93
	v_max3_f32 v188, v188, v94, v95
	v_mov_b32_e32 v189, v188
	s_nop 1
	v_permlane32_swap_b32_e32 v189, v188
	s_waitcnt lgkmcnt(0)
	v_max_f32_e32 v189, v189, v189
	v_mfma_f32_32x32x16_bf16 v[64:79], v[196:199], v[96:99], v[64:79]
	v_max_f32_e32 v188, v188, v189
	v_cmp_gt_f32_e32 vcc, v188, v203
	s_cbranch_vccz .LBB0_1049
	v_max_f32_e32 v188, v188, v188
	v_max_f32_e32 v189, v161, v161
	v_max_f32_e32 v189, v189, v188
	v_sub_f32_e32 v161, v161, v189
	v_exp_f32_e32 v188, v161
	v_mov_b32_e32 v161, v189
	v_mul_f32_e32 v162, v162, v188
	v_pk_mul_f32 v[62:63], v[62:63], v[188:189] op_sel_hi:[1,0]
	v_pk_mul_f32 v[60:61], v[60:61], v[188:189] op_sel_hi:[1,0]
	v_pk_mul_f32 v[58:59], v[58:59], v[188:189] op_sel_hi:[1,0]
	v_pk_mul_f32 v[56:57], v[56:57], v[188:189] op_sel_hi:[1,0]
	v_pk_mul_f32 v[54:55], v[54:55], v[188:189] op_sel_hi:[1,0]
	v_pk_mul_f32 v[52:53], v[52:53], v[188:189] op_sel_hi:[1,0]
	v_pk_mul_f32 v[50:51], v[50:51], v[188:189] op_sel_hi:[1,0]
	v_pk_mul_f32 v[48:49], v[48:49], v[188:189] op_sel_hi:[1,0]
	v_pk_mul_f32 v[46:47], v[46:47], v[188:189] op_sel_hi:[1,0]
	v_pk_mul_f32 v[44:45], v[44:45], v[188:189] op_sel_hi:[1,0]
	v_pk_mul_f32 v[42:43], v[42:43], v[188:189] op_sel_hi:[1,0]
	v_pk_mul_f32 v[40:41], v[40:41], v[188:189] op_sel_hi:[1,0]
	v_pk_mul_f32 v[38:39], v[38:39], v[188:189] op_sel_hi:[1,0]
	v_pk_mul_f32 v[36:37], v[36:37], v[188:189] op_sel_hi:[1,0]
	v_pk_mul_f32 v[34:35], v[34:35], v[188:189] op_sel_hi:[1,0]
	v_pk_mul_f32 v[32:33], v[32:33], v[188:189] op_sel_hi:[1,0]
.LBB0_1049:
	v_pk_add_f32 v[224:225], v[80:81], v[160:161] op_sel:[0,1] op_sel_hi:[1,1] neg_lo:[0,1] neg_hi:[0,1]
	v_pk_add_f32 v[226:227], v[82:83], v[160:161] op_sel:[0,1] op_sel_hi:[1,1] neg_lo:[0,1] neg_hi:[0,1]
	v_pk_add_f32 v[228:229], v[84:85], v[160:161] op_sel:[0,1] op_sel_hi:[1,1] neg_lo:[0,1] neg_hi:[0,1]
	v_pk_add_f32 v[230:231], v[86:87], v[160:161] op_sel:[0,1] op_sel_hi:[1,1] neg_lo:[0,1] neg_hi:[0,1]
	v_pk_add_f32 v[232:233], v[88:89], v[160:161] op_sel:[0,1] op_sel_hi:[1,1] neg_lo:[0,1] neg_hi:[0,1]
	v_pk_add_f32 v[234:235], v[90:91], v[160:161] op_sel:[0,1] op_sel_hi:[1,1] neg_lo:[0,1] neg_hi:[0,1]
	v_pk_add_f32 v[236:237], v[92:93], v[160:161] op_sel:[0,1] op_sel_hi:[1,1] neg_lo:[0,1] neg_hi:[0,1]
	v_pk_add_f32 v[238:239], v[94:95], v[160:161] op_sel:[0,1] op_sel_hi:[1,1] neg_lo:[0,1] neg_hi:[0,1]
	v_exp_f32_e32 v90, v226
	v_exp_f32_e32 v91, v227
	v_exp_f32_e32 v94, v230
	v_exp_f32_e32 v95, v231
	v_exp_f32_e32 v82, v234
	v_exp_f32_e32 v86, v238
	v_exp_f32_e32 v87, v239
	v_exp_f32_e32 v83, v235
	v_exp_f32_e32 v88, v224
	v_exp_f32_e32 v89, v225
	v_exp_f32_e32 v80, v232
	v_exp_f32_e32 v81, v233
	v_pk_add_f32 v[192:193], v[94:95], v[86:87]
	v_pk_add_f32 v[194:195], v[90:91], v[82:83]
	v_pk_add_f32 v[192:193], v[194:195], v[192:193]
	v_max_f32_e32 v194, v65, v65
	v_max_f32_e32 v195, v64, v64
	v_max_f32_e32 v194, v195, v194
	v_max3_f32 v194, v194, v66, v67
	v_max3_f32 v194, v194, v68, v69
	v_exp_f32_e32 v92, v228
	v_exp_f32_e32 v93, v229
	v_exp_f32_e32 v84, v236
	v_exp_f32_e32 v85, v237
	v_max3_f32 v194, v194, v70, v71
	v_max3_f32 v194, v194, v72, v73
	v_max3_f32 v194, v194, v74, v75
	v_max3_f32 v194, v194, v76, v77
	v_pk_add_f32 v[188:189], v[92:93], v[84:85]
	v_pk_add_f32 v[190:191], v[88:89], v[80:81]
	v_max3_f32 v194, v194, v78, v79
	v_mov_b32_e32 v195, v194
	s_nop 1
	v_permlane32_swap_b32_e32 v195, v194
	v_pk_add_f32 v[188:189], v[190:191], v[188:189]
	v_pk_add_f32 v[188:189], v[188:189], v[192:193]
	s_waitcnt lgkmcnt(0)
	v_max_f32_e32 v190, v195, v195
	v_add_f32_e32 v188, v188, v189
	v_mov_b32_e32 v189, v188
	s_nop 1
	v_permlane32_swap_b32_e32 v189, v188
	v_max_f32_e32 v190, v194, v190
	v_cmp_gt_f32_e32 vcc, v190, v204
	s_cbranch_vccz .LBB0_1051
	v_max_f32_e32 v190, v190, v190
	v_max_f32_e32 v191, v167, v167
	v_max_f32_e32 v191, v191, v190
	v_sub_f32_e32 v167, v167, v191
	v_exp_f32_e32 v190, v167
	v_mov_b32_e32 v167, v191
	v_mul_f32_e32 v160, v160, v190
	v_pk_mul_f32 v[30:31], v[30:31], v[190:191] op_sel_hi:[1,0]
	v_pk_mul_f32 v[28:29], v[28:29], v[190:191] op_sel_hi:[1,0]
	v_pk_mul_f32 v[26:27], v[26:27], v[190:191] op_sel_hi:[1,0]
	v_pk_mul_f32 v[24:25], v[24:25], v[190:191] op_sel_hi:[1,0]
	v_pk_mul_f32 v[22:23], v[22:23], v[190:191] op_sel_hi:[1,0]
	v_pk_mul_f32 v[20:21], v[20:21], v[190:191] op_sel_hi:[1,0]
	v_pk_mul_f32 v[18:19], v[18:19], v[190:191] op_sel_hi:[1,0]
	v_pk_mul_f32 v[16:17], v[16:17], v[190:191] op_sel_hi:[1,0]
	v_pk_mul_f32 v[14:15], v[14:15], v[190:191] op_sel_hi:[1,0]
	v_pk_mul_f32 v[12:13], v[12:13], v[190:191] op_sel_hi:[1,0]
	v_pk_mul_f32 v[10:11], v[10:11], v[190:191] op_sel_hi:[1,0]
	v_pk_mul_f32 v[8:9], v[8:9], v[190:191] op_sel_hi:[1,0]
	v_pk_mul_f32 v[6:7], v[6:7], v[190:191] op_sel_hi:[1,0]
	v_pk_mul_f32 v[4:5], v[4:5], v[190:191] op_sel_hi:[1,0]
	v_pk_mul_f32 v[2:3], v[2:3], v[190:191] op_sel_hi:[1,0]
	v_pk_mul_f32 v[0:1], v[0:1], v[190:191] op_sel_hi:[1,0]
